# de-phase with 2 sub-groups (pairs of A-sharing classes) 3us apart instead of 4 sub-groups 2.5us apart
# speedup vs baseline: 1.0350x; 1.0000x over previous
.LBB0_402:
	v_writelane_b32 v252, s14, 54
	v_writelane_b32 v252, s86, 56
	s_nop 1
	v_writelane_b32 v252, s87, 57
	v_writelane_b32 v252, s84, 58
	s_nop 1
	v_writelane_b32 v252, s85, 59
	v_writelane_b32 v252, s68, 60
	s_nop 1
	v_writelane_b32 v253, s72, 0
	v_writelane_b32 v252, s69, 61
	v_writelane_b32 v253, s73, 1
	v_writelane_b32 v252, s70, 62
	v_writelane_b32 v253, s74, 2
	v_writelane_b32 v252, s71, 63
	v_writelane_b32 v253, s75, 3
	s_or_b64 exec, exec, s[0:1]
	s_add_u32 s18, s76, 0xa000000
	s_addc_u32 s19, s77, 0
	s_cmpk_lt_i32 s26, 0xe80
	s_cselect_b64 s[0:1], -1, 0
	s_add_u32 s15, s76, 0x7800000
	s_addc_u32 s88, s77, 0
	v_writelane_b32 v253, s0, 4
	s_add_u32 s89, s76, 0x8000000
	s_addc_u32 s90, s77, 0
	v_writelane_b32 v253, s1, 5
	s_bfe_u32 s0, s82, 0x20006
	s_lshr_b32 s1, s82, 8
	s_cmp_eq_u32 s1, 1
	s_cselect_b64 s[10:11], -1, 0
	s_lshl_b32 s2, s1, 6
	s_lshl_b32 s17, s1, 13
	s_or_b32 s1, s2, 16
	v_writelane_b32 v253, s1, 6
	s_lshl_b32 s65, s1, 7
	s_or_b32 s1, s2, 32
	v_writelane_b32 v253, s1, 7
	s_lshl_b32 s1, s1, 7
	v_writelane_b32 v253, s1, 8
	v_writelane_b32 v253, s2, 10
	s_or_b32 s1, s2, 48
	v_writelane_b32 v253, s1, 11
	s_lshl_b32 s1, s1, 7
	s_lshl_b32 s64, s0, 12
	v_writelane_b32 v253, s1, 12
	s_mov_b32 s2, s82
	v_writelane_b32 v253, s2, 14
	s_cmpk_lt_u32 s82, 0x100
	v_cndmask_b32_e64 v192, 0, 1, s[10:11]
	v_writelane_b32 v253, s3, 15
	s_cselect_b64 s[2:3], -1, 0
	v_writelane_b32 v253, s2, 16
	s_lshl_b32 s0, s0, 5
	s_barrier
	v_writelane_b32 v253, s3, 17
	v_writelane_b32 v253, s0, 18
	s_add_u32 s0, s76, 0x12000000
	s_addc_u32 s1, s77, 0
	v_writelane_b32 v253, s0, 19
	s_cmpk_gt_i32 s26, 0xe7f
	s_nop 0
	v_writelane_b32 v253, s1, 20
	s_mov_b32 s0, s26
	v_writelane_b32 v253, s0, 21
	s_mov_b32 s26, s80
	s_nop 0
	v_writelane_b32 v253, s1, 22
	v_writelane_b32 v253, s27, 23
	s_cbranch_scc1 .LBB0_549
	s_add_u32 s91, s76, 0x5800000
	v_readlane_b32 s0, v253, 8
	s_addc_u32 s92, s77, 0
	s_add_i32 s96, s0, 0
	v_readlane_b32 s0, v253, 12
	s_add_i32 s25, s64, 0
	s_add_i32 s97, s0, 0
	v_readlane_b32 s0, v253, 21
	s_mov_b32 s23, 0
	s_add_i32 s93, s25, 0x10000
	s_add_i32 s94, s17, 0
	s_add_i32 s95, s65, 0
	s_add_i32 s12, s25, 0x14000
	s_add_i32 s13, s25, 0x18000
	s_add_i32 s25, s25, 0x1c000
	s_add_i32 s33, s0, 0xfffff200
	s_lshl_b32 s84, s0, 8
	s_lshl_b32 s85, s80, 8
	s_mov_b64 s[44:45], 0x80
	s_mov_b64 s[46:47], 0x5800080
	s_mov_b64 s[48:49], 0x4900100
	s_mov_b64 s[50:51], 0x5800100
	s_mov_b64 s[52:53], 0x4980100
	s_mov_b64 s[54:55], 0x4900180
	s_mov_b64 s[56:57], 0x5800180
	s_mov_b64 s[58:59], 0x4980180
	s_mov_b64 s[60:61], 0x100
	s_mov_b64 s[62:63], 0xf80
	v_mov_b32_e32 v129, 0
	s_mov_b64 s[66:67], 0xa000080
	s_mov_b64 s[68:69], 0xa000100
	s_mov_b64 s[70:71], 0x80100
	s_mov_b64 s[72:73], 0x180
	s_mov_b64 s[74:75], 0xa000180
	s_mov_b64 s[8:9], 0x80180
	s_movk_i32 s86, 0x3800
	v_mov_b32_e32 v146, 1
	v_mov_b32_e32 v147, 0x1000
	v_mov_b32_e32 v148, 0x2000
	v_mov_b32_e32 v149, 0x3000
	v_readlane_b32 s87, v252, 54
	s_mov_b32 s40, s0
	v_readlane_b32 s1, v253, 22
	s_cmpk_lt_u32 s40, 0x80
	s_cbranch_scc1 .Lp1_lo
	s_mov_b32 s98, 62
	s_bfe_u32 s99, s40, 0x10004
	s_mul_i32 s99, s99, 6
	s_add_u32 s98, s98, s99
	s_branch .Lp1_go
.Lp1_lo:
	s_mov_b32 s98, 0
	s_bfe_u32 s99, s40, 0x10004
	s_mul_i32 s99, s99, 6
	s_add_u32 s98, s98, s99

.LBB0_627:
	s_add_u32 s0, s76, 0x2e000000
	s_addc_u32 s1, s77, 0
	v_writelane_b32 v253, s0, 40
	s_add_u32 s2, s76, 0x22000000
	s_addc_u32 s3, s77, 0
	v_writelane_b32 v253, s1, 41
	s_nop 0
	v_readlane_b32 s0, v253, 4
	v_readlane_b32 s1, v253, 5
	s_andn2_b64 vcc, exec, s[0:1]
	s_barrier
	s_cbranch_vccnz .LBB0_691
	v_readlane_b32 s0, v253, 28
	s_add_i32 s57, s0, 0
	v_readlane_b32 s0, v253, 30
	s_add_i32 s58, s0, 0
	v_readlane_b32 s0, v253, 8
	s_add_i32 s63, s64, 0
	s_add_i32 s59, s0, 0
	v_readlane_b32 s0, v253, 12
	s_mov_b32 s9, 0
	s_add_i32 s56, s63, 0x10000
	s_add_i32 s60, s0, 0
	s_add_i32 s61, s63, 0x14000
	s_add_i32 s62, s63, 0x18000
	s_add_i32 s63, s63, 0x1c000
	s_add_i32 s66, s78, 0xfffffa00
	s_lshl_b32 s67, s78, 8
	s_lshl_b32 s68, s80, 8
	s_add_i32 s69, 0, 0x10000
	s_add_i32 s70, 0, 0x14000
	s_mov_b64 s[12:13], 0x80
	s_mov_b64 s[14:15], 0x12000080
	s_mov_b64 s[16:17], 0x3000100
	s_mov_b64 s[18:19], 0x12000100
	s_mov_b64 s[20:21], 0x3080100
	s_mov_b64 s[22:23], 0x3000180
	s_mov_b64 s[36:37], 0x12000180
	s_mov_b64 s[38:39], 0x3080180
	s_mov_b64 s[40:41], 0x100
	s_mov_b64 s[42:43], 0xf80
	s_movk_i32 s71, 0x1080
	s_movk_i32 s72, 0x2100
	s_mov_b64 s[44:45], 0x2400100
	s_mov_b64 s[46:47], 0x2480100
	s_mov_b64 s[48:49], 0x2400180
	s_mov_b64 s[50:51], 0x2480180
	s_movk_i32 s73, 0x1800
	v_mov_b32_e32 v129, 0
	v_mov_b32_e32 v146, 1
	s_mov_b32 s74, s78
	s_mov_b32 s75, s78
	s_cmpk_lt_u32 s75, 0x80
	s_cbranch_scc1 .Lp6_lo
	s_mov_b32 s98, 62
	s_bfe_u32 s99, s75, 0x10004
	s_mul_i32 s99, s99, 6
	s_add_u32 s98, s98, s99
	s_branch .Lp6_go
.Lp6_lo:
	s_mov_b32 s98, 0
	s_bfe_u32 s99, s75, 0x10004
	s_mul_i32 s99, s99, 6
	s_add_u32 s98, s98, s99
